# fused-LN epilogue: residual H loads issued in rolling batches (counted vmcnt) instead of one load per vmcnt(0)
# speedup vs baseline: 1.0036x; 1.0036x over previous
; #define EPI_ROWS(ai, m) _Pragma("unroll") for (int ai = 0; ai < 2; ++ai) _Pragma("unroll") for (int m = 0; m < 4; ++m)
; #define EPI_COLS(bj, n) _Pragma("unroll") for (int bj = 0; bj < 2; ++bj) _Pragma("unroll") for (int n = 0; n < 2; ++n)
;     __device__ __forceinline__ void fused(Acc& acc, const Unit& u, int wr, int wc, int fr, int fq) const {
;     ...
;         { const float* gp = gate + (size_t)((u.pm * 256) >> 11) * MODW + colb;
;           EPI_COLS(bj, n) gv[bj][n] = *(const f32x4*)(gp + bj * 128 + n * 16); }
;         EPI_ROWS(ai, m) { const int row = u.pm * 256 + ai * 128 + wr * 64 + m * 16 + fr; const float* hp = H + (size_t)row * D + colb;
;             EPI_COLS(bj, n) { const int co = bj * 128 + n * 16; acc[ai][bj][m][n] = *(const f32x4*)(hp + co) * ALPHA + gv[bj][n] * acc[ai][bj][m][n]; }
.LBB0_1592:
	s_waitcnt vmcnt(0)
	s_barrier
	s_lshl_b32 s2, s38, 8
	s_lshl_b32 s3, s39, 5
	s_add_i32 s3, s3, s2
	s_ashr_i32 s2, s30, 3
	s_mul_i32 s46, s2, 0xc000
	s_mul_hi_i32 s24, s2, 0xc000
	s_add_u32 s2, s60, s46
	v_lshl_add_u32 v190, v155, 2, s3
	s_addc_u32 s3, s61, s24
	s_lshl_b32 s40, s30, 8
	v_lshl_add_u32 v0, s31, 6, v154
	v_ashrrev_i32_e32 v191, 31, v190
	v_add_u32_e32 v200, s40, v0
	v_lshlrev_b64 v[178:179], 2, v[190:191]
	v_ashrrev_i32_e32 v201, 31, v200
	v_lshl_add_u64 v[122:123], s[2:3], 0, v[178:179]
	v_lshlrev_b64 v[206:207], 13, v[200:201]
	global_load_dwordx4 v[150:153], v[122:123], off
	global_load_dwordx4 v[146:149], v[122:123], off offset:64
	global_load_dwordx4 v[142:145], v[122:123], off offset:512
	global_load_dwordx4 v[138:141], v[122:123], off offset:576
	v_add_u32_e32 v180, 16, v200
	v_ashrrev_i32_e32 v181, 31, v180
	v_lshlrev_b64 v[182:183], 13, v[180:181]
	v_add_u32_e32 v184, 32, v200
	v_ashrrev_i32_e32 v185, 31, v184
	v_lshlrev_b64 v[186:187], 13, v[184:185]
	v_add_u32_e32 v188, 48, v200
	v_ashrrev_i32_e32 v189, 31, v188
	v_lshlrev_b64 v[198:199], 13, v[188:189]
	v_add_u32_e32 v202, 0x80, v200
	v_ashrrev_i32_e32 v203, 31, v202
	v_lshlrev_b64 v[204:205], 13, v[202:203]
	v_add_u32_e32 v208, 0x90, v200
	v_ashrrev_i32_e32 v209, 31, v208
	v_lshlrev_b64 v[210:211], 13, v[208:209]
	v_add_u32_e32 v212, 0xa0, v200
	v_ashrrev_i32_e32 v213, 31, v212
	v_lshlrev_b64 v[214:215], 13, v[212:213]
	v_add_u32_e32 v216, 0xb0, v200
	v_ashrrev_i32_e32 v217, 31, v216
	v_lshlrev_b64 v[218:219], 13, v[216:217]
	s_lshl_b32 s2, s39, 3
	s_add_i32 s14, s2, 0
	v_cmp_eq_u32_e32 vcc, 0, v155
	s_add_i32 s14, s14, 0x20000
	v_lshl_add_u64 v[196:197], s[70:71], 0, v[206:207]
	v_lshl_add_u64 v[196:197], v[196:197], 0, v[178:179]
	global_load_dwordx4 v[158:161], v[196:197], off
	global_load_dwordx4 v[162:165], v[196:197], off offset:64
	global_load_dwordx4 v[166:169], v[196:197], off offset:512
	global_load_dwordx4 v[170:173], v[196:197], off offset:576
	v_lshl_add_u64 v[196:197], s[70:71], 0, v[182:183]
	v_lshl_add_u64 v[196:197], v[196:197], 0, v[178:179]
	global_load_dwordx4 v[174:177], v[196:197], off
	global_load_dwordx4 v[192:195], v[196:197], off offset:64
	global_load_dwordx4 v[220:223], v[196:197], off offset:512
	global_load_dwordx4 v[224:227], v[196:197], off offset:576
	s_waitcnt vmcnt(4)
	v_pk_mul_f32 v[124:125], v[160:161], s[84:85] op_sel_hi:[1,0]
	v_pk_mul_f32 v[122:123], v[158:159], s[84:85] op_sel_hi:[1,0]
	v_pk_fma_f32 v[64:65], v[64:65], v[152:153], v[124:125]
	v_pk_fma_f32 v[62:63], v[62:63], v[150:151], v[122:123]
	v_pk_mul_f32 v[124:125], v[164:165], s[84:85] op_sel_hi:[1,0]
	v_pk_mul_f32 v[122:123], v[162:163], s[84:85] op_sel_hi:[1,0]
	v_pk_fma_f32 v[44:45], v[44:45], v[148:149], v[124:125]
	v_pk_fma_f32 v[42:43], v[42:43], v[146:147], v[122:123]
	v_pk_mul_f32 v[124:125], v[168:169], s[84:85] op_sel_hi:[1,0]
	v_pk_mul_f32 v[122:123], v[166:167], s[84:85] op_sel_hi:[1,0]
	v_pk_fma_f32 v[36:37], v[36:37], v[144:145], v[124:125]
	v_pk_fma_f32 v[34:35], v[34:35], v[142:143], v[122:123]
	v_pk_mul_f32 v[122:123], v[170:171], s[84:85] op_sel_hi:[1,0]
	v_pk_mul_f32 v[124:125], v[172:173], s[84:85] op_sel_hi:[1,0]
	v_lshl_add_u64 v[196:197], s[70:71], 0, v[186:187]
	v_lshl_add_u64 v[196:197], v[196:197], 0, v[178:179]
	global_load_dwordx4 v[158:161], v[196:197], off
	global_load_dwordx4 v[162:165], v[196:197], off offset:64
	global_load_dwordx4 v[166:169], v[196:197], off offset:512
	global_load_dwordx4 v[170:173], v[196:197], off offset:576
	v_pk_fma_f32 v[2:3], v[2:3], v[138:139], v[122:123]
	v_pk_fma_f32 v[4:5], v[4:5], v[140:141], v[124:125]
	s_waitcnt vmcnt(4)
	v_pk_mul_f32 v[124:125], v[176:177], s[84:85] op_sel_hi:[1,0]
	v_pk_mul_f32 v[122:123], v[174:175], s[84:85] op_sel_hi:[1,0]
	v_pk_fma_f32 v[20:21], v[20:21], v[152:153], v[124:125]
	v_pk_fma_f32 v[18:19], v[18:19], v[150:151], v[122:123]
	v_pk_mul_f32 v[124:125], v[194:195], s[84:85] op_sel_hi:[1,0]
	v_pk_mul_f32 v[122:123], v[192:193], s[84:85] op_sel_hi:[1,0]
	v_pk_fma_f32 v[16:17], v[16:17], v[148:149], v[124:125]
	v_pk_fma_f32 v[14:15], v[14:15], v[146:147], v[122:123]
	v_pk_mul_f32 v[124:125], v[222:223], s[84:85] op_sel_hi:[1,0]
	v_pk_mul_f32 v[122:123], v[220:221], s[84:85] op_sel_hi:[1,0]
	v_pk_fma_f32 v[12:13], v[12:13], v[144:145], v[124:125]
	v_pk_fma_f32 v[10:11], v[10:11], v[142:143], v[122:123]
	v_pk_mul_f32 v[122:123], v[224:225], s[84:85] op_sel_hi:[1,0]
	v_pk_mul_f32 v[124:125], v[226:227], s[84:85] op_sel_hi:[1,0]
	v_lshl_add_u64 v[196:197], s[70:71], 0, v[198:199]
	v_lshl_add_u64 v[196:197], v[196:197], 0, v[178:179]
	global_load_dwordx4 v[174:177], v[196:197], off
	global_load_dwordx4 v[192:195], v[196:197], off offset:64
	global_load_dwordx4 v[220:223], v[196:197], off offset:512
	global_load_dwordx4 v[224:227], v[196:197], off offset:576
	v_pk_fma_f32 v[6:7], v[6:7], v[138:139], v[122:123]
	v_pk_fma_f32 v[8:9], v[8:9], v[140:141], v[124:125]
	s_waitcnt vmcnt(4)
	v_pk_mul_f32 v[124:125], v[160:161], s[84:85] op_sel_hi:[1,0]
	v_pk_mul_f32 v[122:123], v[158:159], s[84:85] op_sel_hi:[1,0]
	v_pk_fma_f32 v[40:41], v[40:41], v[152:153], v[124:125]
	v_pk_fma_f32 v[38:39], v[38:39], v[150:151], v[122:123]
	v_pk_mul_f32 v[124:125], v[164:165], s[84:85] op_sel_hi:[1,0]
	v_pk_mul_f32 v[122:123], v[162:163], s[84:85] op_sel_hi:[1,0]
	v_pk_fma_f32 v[32:33], v[32:33], v[148:149], v[124:125]
	v_pk_fma_f32 v[30:31], v[30:31], v[146:147], v[122:123]
	v_pk_mul_f32 v[124:125], v[168:169], s[84:85] op_sel_hi:[1,0]
	v_pk_mul_f32 v[122:123], v[166:167], s[84:85] op_sel_hi:[1,0]
	v_pk_fma_f32 v[28:29], v[28:29], v[144:145], v[124:125]
	v_pk_fma_f32 v[26:27], v[26:27], v[142:143], v[122:123]
	v_pk_mul_f32 v[122:123], v[170:171], s[84:85] op_sel_hi:[1,0]
	v_pk_mul_f32 v[124:125], v[172:173], s[84:85] op_sel_hi:[1,0]
	v_lshl_add_u64 v[196:197], s[70:71], 0, v[204:205]
	v_lshl_add_u64 v[196:197], v[196:197], 0, v[178:179]
	global_load_dwordx4 v[158:161], v[196:197], off
	global_load_dwordx4 v[162:165], v[196:197], off offset:64
	global_load_dwordx4 v[166:169], v[196:197], off offset:512
	global_load_dwordx4 v[170:173], v[196:197], off offset:576
	v_pk_fma_f32 v[22:23], v[22:23], v[138:139], v[122:123]
	v_pk_fma_f32 v[24:25], v[24:25], v[140:141], v[124:125]
	s_waitcnt vmcnt(4)
; #define EPI_ROWS(ai, m) _Pragma("unroll") for (int ai = 0; ai < 2; ++ai) _Pragma("unroll") for (int m = 0; m < 4; ++m)
; #define EPI_COLS(bj, n) _Pragma("unroll") for (int bj = 0; bj < 2; ++bj) _Pragma("unroll") for (int n = 0; n < 2; ++n)
;     __device__ __forceinline__ void fused(Acc& acc, const Unit& u, int wr, int wc, int fr, int fq) const {
;     ...
;         EPI_ROWS(ai, m) { const int row = u.pm * 256 + ai * 128 + wr * 64 + m * 16 + fr; const float* hp = H + (size_t)row * D + colb;
;             EPI_COLS(bj, n) { const int co = bj * 128 + n * 16; acc[ai][bj][m][n] = *(const f32x4*)(hp + co) * ALPHA + gv[bj][n] * acc[ai][bj][m][n]; }
	v_pk_mul_f32 v[124:125], v[176:177], s[84:85] op_sel_hi:[1,0]
	v_pk_mul_f32 v[122:123], v[174:175], s[84:85] op_sel_hi:[1,0]
	v_pk_fma_f32 v[60:61], v[60:61], v[152:153], v[124:125]
	v_pk_fma_f32 v[58:59], v[58:59], v[150:151], v[122:123]
	v_pk_mul_f32 v[124:125], v[194:195], s[84:85] op_sel_hi:[1,0]
	v_pk_mul_f32 v[122:123], v[192:193], s[84:85] op_sel_hi:[1,0]
	v_pk_fma_f32 v[56:57], v[56:57], v[148:149], v[124:125]
	v_pk_fma_f32 v[54:55], v[54:55], v[146:147], v[122:123]
	v_pk_mul_f32 v[124:125], v[222:223], s[84:85] op_sel_hi:[1,0]
	v_pk_mul_f32 v[122:123], v[220:221], s[84:85] op_sel_hi:[1,0]
	v_pk_fma_f32 v[52:53], v[52:53], v[144:145], v[124:125]
	v_pk_fma_f32 v[50:51], v[50:51], v[142:143], v[122:123]
	v_pk_mul_f32 v[124:125], v[226:227], s[84:85] op_sel_hi:[1,0]
	v_pk_mul_f32 v[122:123], v[224:225], s[84:85] op_sel_hi:[1,0]
	v_lshl_add_u64 v[196:197], s[70:71], 0, v[210:211]
	v_lshl_add_u64 v[196:197], v[196:197], 0, v[178:179]
	global_load_dwordx4 v[174:177], v[196:197], off
	global_load_dwordx4 v[192:195], v[196:197], off offset:64
	global_load_dwordx4 v[220:223], v[196:197], off offset:512
	global_load_dwordx4 v[224:227], v[196:197], off offset:576
	v_pk_fma_f32 v[48:49], v[48:49], v[140:141], v[124:125]
	v_pk_fma_f32 v[46:47], v[46:47], v[138:139], v[122:123]
	s_waitcnt vmcnt(4)
	v_pk_mul_f32 v[124:125], v[160:161], s[84:85] op_sel_hi:[1,0]
	v_pk_mul_f32 v[122:123], v[158:159], s[84:85] op_sel_hi:[1,0]
	v_pk_fma_f32 v[80:81], v[80:81], v[152:153], v[124:125]
	v_pk_fma_f32 v[78:79], v[78:79], v[150:151], v[122:123]
	v_pk_mul_f32 v[124:125], v[164:165], s[84:85] op_sel_hi:[1,0]
	v_pk_mul_f32 v[122:123], v[162:163], s[84:85] op_sel_hi:[1,0]
	v_pk_fma_f32 v[76:77], v[76:77], v[148:149], v[124:125]
	v_pk_fma_f32 v[74:75], v[74:75], v[146:147], v[122:123]
	v_pk_mul_f32 v[124:125], v[168:169], s[84:85] op_sel_hi:[1,0]
	v_pk_mul_f32 v[122:123], v[166:167], s[84:85] op_sel_hi:[1,0]
	v_pk_fma_f32 v[72:73], v[72:73], v[144:145], v[124:125]
	v_pk_fma_f32 v[70:71], v[70:71], v[142:143], v[122:123]
	v_pk_mul_f32 v[122:123], v[170:171], s[84:85] op_sel_hi:[1,0]
	v_pk_mul_f32 v[124:125], v[172:173], s[84:85] op_sel_hi:[1,0]
	v_lshl_add_u64 v[196:197], s[70:71], 0, v[214:215]
	v_lshl_add_u64 v[196:197], v[196:197], 0, v[178:179]
	global_load_dwordx4 v[158:161], v[196:197], off
	global_load_dwordx4 v[162:165], v[196:197], off offset:64
	global_load_dwordx4 v[166:169], v[196:197], off offset:512
	global_load_dwordx4 v[170:173], v[196:197], off offset:576
	v_pk_fma_f32 v[66:67], v[66:67], v[138:139], v[122:123]
	v_pk_fma_f32 v[68:69], v[68:69], v[140:141], v[124:125]
	s_waitcnt vmcnt(4)
	v_pk_mul_f32 v[124:125], v[176:177], s[84:85] op_sel_hi:[1,0]
	v_pk_mul_f32 v[122:123], v[174:175], s[84:85] op_sel_hi:[1,0]
	v_pk_fma_f32 v[100:101], v[100:101], v[152:153], v[124:125]
	v_pk_fma_f32 v[98:99], v[98:99], v[150:151], v[122:123]
	v_pk_mul_f32 v[124:125], v[194:195], s[84:85] op_sel_hi:[1,0]
	v_pk_mul_f32 v[122:123], v[192:193], s[84:85] op_sel_hi:[1,0]
	v_pk_fma_f32 v[96:97], v[96:97], v[148:149], v[124:125]
	v_pk_fma_f32 v[94:95], v[94:95], v[146:147], v[122:123]
	v_pk_mul_f32 v[124:125], v[222:223], s[84:85] op_sel_hi:[1,0]
	v_pk_mul_f32 v[122:123], v[220:221], s[84:85] op_sel_hi:[1,0]
	v_pk_fma_f32 v[92:93], v[92:93], v[144:145], v[124:125]
	v_pk_fma_f32 v[90:91], v[90:91], v[142:143], v[122:123]
	v_pk_mul_f32 v[122:123], v[224:225], s[84:85] op_sel_hi:[1,0]
	v_pk_mul_f32 v[124:125], v[226:227], s[84:85] op_sel_hi:[1,0]
	v_lshl_add_u64 v[196:197], s[70:71], 0, v[218:219]
	v_lshl_add_u64 v[196:197], v[196:197], 0, v[178:179]
	global_load_dwordx4 v[174:177], v[196:197], off
	global_load_dwordx4 v[192:195], v[196:197], off offset:64
	global_load_dwordx4 v[220:223], v[196:197], off offset:512
	global_load_dwordx4 v[224:227], v[196:197], off offset:576
	v_pk_fma_f32 v[86:87], v[86:87], v[138:139], v[122:123]
	v_pk_fma_f32 v[88:89], v[88:89], v[140:141], v[124:125]
	s_waitcnt vmcnt(4)
; __device__ __forceinline__ float shx(float v, int mask, int lane) { return __int_as_float(__builtin_amdgcn_ds_bpermute((lane ^ mask) << 2, __float_as_int(v))); }
; #define EPI_ROWS(ai, m) _Pragma("unroll") for (int ai = 0; ai < 2; ++ai) _Pragma("unroll") for (int m = 0; m < 4; ++m)
; #define EPI_COLS(bj, n) _Pragma("unroll") for (int bj = 0; bj < 2; ++bj) _Pragma("unroll") for (int n = 0; n < 2; ++n)
;     __device__ __forceinline__ void run(const Acc& v, const Unit& u, int wr, int wc, int fr, int fq, LAS unsigned char* sl, int wid, int lane) const {
;     ...
;                 float sm = 0.f;
; #pragma unroll
;                 for (int bj = 0; bj < 2; ++bj)
; #pragma unroll
;                     for (int n = 0; n < 2; ++n) { const f32x4 x = v[ai][bj][m][n]; sm += (x[0] + x[1]) + (x[2] + x[3]); }
;                 sm += shx(sm, 16, lane); sm += shx(sm, 32, lane);
;                 const float mw = sm * (1.0f / 64.0f); float q = 0.f;
; #pragma unroll
;                 for (int bj = 0; bj < 2; ++bj)
; #pragma unroll
;                     for (int n = 0; n < 2; ++n) { const f32x4 d = v[ai][bj][m][n] - mw; q += (d[0] * d[0] + d[1] * d[1]) + (d[2] * d[2] + d[3] * d[3]); }
;                 q += shx(q, 16, lane); q += shx(q, 32, lane);
;                 if (fq == 0) P[(ai * 128 + wr * 64 + m * 16 + fr) * 4 + wc] = (f32x2){mw, q};
;     __device__ __forceinline__ void fused(Acc& acc, const Unit& u, int wr, int wc, int fr, int fq) const {
;     ...
;         EPI_ROWS(ai, m) { const int row = u.pm * 256 + ai * 128 + wr * 64 + m * 16 + fr; const float* hp = H + (size_t)row * D + colb;
;             EPI_COLS(bj, n) { const int co = bj * 128 + n * 16; acc[ai][bj][m][n] = *(const f32x4*)(hp + co) * ALPHA + gv[bj][n] * acc[ai][bj][m][n]; }
	v_pk_mul_f32 v[124:125], v[160:161], s[84:85] op_sel_hi:[1,0]
	v_pk_mul_f32 v[122:123], v[158:159], s[84:85] op_sel_hi:[1,0]
	v_pk_fma_f32 v[128:129], v[120:121], v[152:153], v[124:125]
	v_pk_fma_f32 v[126:127], v[118:119], v[150:151], v[122:123]
	v_pk_mul_f32 v[120:121], v[164:165], s[84:85] op_sel_hi:[1,0]
	v_pk_mul_f32 v[118:119], v[162:163], s[84:85] op_sel_hi:[1,0]
	v_pk_fma_f32 v[124:125], v[116:117], v[148:149], v[120:121]
	v_pk_fma_f32 v[122:123], v[114:115], v[146:147], v[118:119]
	v_pk_mul_f32 v[116:117], v[168:169], s[84:85] op_sel_hi:[1,0]
	v_pk_mul_f32 v[114:115], v[166:167], s[84:85] op_sel_hi:[1,0]
	v_pk_fma_f32 v[120:121], v[112:113], v[144:145], v[116:117]
	v_pk_fma_f32 v[118:119], v[110:111], v[142:143], v[114:115]
	v_pk_mul_f32 v[110:111], v[170:171], s[84:85] op_sel_hi:[1,0]
	v_pk_mul_f32 v[112:113], v[172:173], s[84:85] op_sel_hi:[1,0]
	v_pk_fma_f32 v[114:115], v[106:107], v[138:139], v[110:111]
	v_pk_fma_f32 v[116:117], v[108:109], v[140:141], v[112:113]
	s_waitcnt vmcnt(0)
	v_pk_mul_f32 v[108:109], v[176:177], s[84:85] op_sel_hi:[1,0]
	v_pk_mul_f32 v[106:107], v[174:175], s[84:85] op_sel_hi:[1,0]
	v_pk_fma_f32 v[112:113], v[136:137], v[152:153], v[108:109]
	v_pk_fma_f32 v[110:111], v[134:135], v[150:151], v[106:107]
	v_mov_b32_e32 v134, v63
	v_mov_b32_e32 v135, v64
	v_mov_b32_e32 v136, v62
	v_mov_b32_e32 v137, v65
	v_pk_add_f32 v[134:135], v[134:135], v[136:137]
	v_mov_b32_e32 v136, v43
	v_mov_b32_e32 v137, v44
	v_pk_mul_f32 v[108:109], v[194:195], s[84:85] op_sel_hi:[1,0]
	v_pk_mul_f32 v[106:107], v[192:193], s[84:85] op_sel_hi:[1,0]
	v_pk_fma_f32 v[108:109], v[132:133], v[148:149], v[108:109]
	v_pk_fma_f32 v[106:107], v[130:131], v[146:147], v[106:107]
	v_pk_mul_f32 v[132:133], v[222:223], s[84:85] op_sel_hi:[1,0]
	v_pk_mul_f32 v[130:131], v[220:221], s[84:85] op_sel_hi:[1,0]
	v_pk_fma_f32 v[104:105], v[104:105], v[144:145], v[132:133]
	v_pk_fma_f32 v[102:103], v[102:103], v[142:143], v[130:131]
	v_pk_mul_f32 v[130:131], v[224:225], s[84:85] op_sel_hi:[1,0]
	s_nop 0
	v_pk_fma_f32 v[82:83], v[82:83], v[138:139], v[130:131]
	v_mov_b32_e32 v138, v42
	v_mov_b32_e32 v139, v45
	v_pk_mul_f32 v[132:133], v[226:227], s[84:85] op_sel_hi:[1,0]
	v_pk_add_f32 v[136:137], v[136:137], v[138:139]
	v_pk_fma_f32 v[84:85], v[84:85], v[140:141], v[132:133]
	v_add_f32_e32 v133, v134, v135
	v_pk_add_f32 v[136:137], v[136:137], v[136:137] op_sel_hi:[0,1]
	v_add_f32_e32 v135, 0, v133
	v_add_f32_e32 v139, v34, v35
	v_add_f32_e32 v141, v36, v37
	v_mov_b32_e32 v138, v2
	v_mov_b32_e32 v140, v3
	v_mov_b32_e32 v136, v4
	v_mov_b32_e32 v134, v5
	v_lshl_add_u32 v132, v155, 4, v154
	v_pk_add_f32 v[138:139], v[138:139], v[140:141]
	v_pk_add_f32 v[134:135], v[136:137], v[134:135]
	v_lshlrev_b32_e32 v130, 2, v132
	v_pk_add_f32 v[134:135], v[138:139], v[134:135]
	v_xor_b32_e32 v131, 64, v130
	v_add_f32_e32 v133, v134, v135
	ds_bpermute_b32 v134, v131, v133
	v_xor_b32_e32 v130, 0x80, v130
	s_waitcnt lgkmcnt(0)
	v_add_f32_e32 v133, v133, v134
	ds_bpermute_b32 v134, v130, v133
	s_waitcnt lgkmcnt(0)
	v_add_f32_e32 v133, v133, v134
	v_fmamk_f32 v135, v133, 0xbc800000, v65
	v_fmamk_f32 v137, v133, 0xbc800000, v63
	v_fmamk_f32 v134, v133, 0xbc800000, v64
	v_fmamk_f32 v136, v133, 0xbc800000, v62
	v_mul_f32_e32 v137, v137, v137
	v_mul_f32_e32 v135, v135, v135
	v_fmac_f32_e32 v137, v136, v136
	v_fmac_f32_e32 v135, v134, v134
	v_fmamk_f32 v136, v133, 0xbc800000, v45
	v_fmamk_f32 v138, v133, 0xbc800000, v43
	v_add_f32_e32 v134, v137, v135
	v_fmamk_f32 v135, v133, 0xbc800000, v44
	v_fmamk_f32 v137, v133, 0xbc800000, v42
	v_mul_f32_e32 v138, v138, v138
	v_mul_f32_e32 v136, v136, v136
	v_fmac_f32_e32 v138, v137, v137
	v_fmac_f32_e32 v136, v135, v135
	v_add_f32_e32 v135, v138, v136
	v_fmamk_f32 v136, v133, 0xbc800000, v37
	v_fmamk_f32 v138, v133, 0xbc800000, v35
	v_add_f32_e32 v134, v134, v135
	v_fmamk_f32 v135, v133, 0xbc800000, v36
	v_fmamk_f32 v137, v133, 0xbc800000, v34
	v_mul_f32_e32 v138, v138, v138
	v_mul_f32_e32 v136, v136, v136
	v_fmac_f32_e32 v138, v137, v137
	v_fmac_f32_e32 v136, v135, v135
	v_add_f32_e32 v135, v138, v136
	v_fmamk_f32 v136, v133, 0xbc800000, v5
	v_fmamk_f32 v138, v133, 0xbc800000, v3
	v_add_f32_e32 v134, v135, v134
	v_fmamk_f32 v135, v133, 0xbc800000, v4
	v_fmamk_f32 v137, v133, 0xbc800000, v2
	v_mul_f32_e32 v138, v138, v138
	v_mul_f32_e32 v136, v136, v136
	v_fmac_f32_e32 v138, v137, v137
	v_fmac_f32_e32 v136, v135, v135
	v_add_f32_e32 v135, v138, v136
	v_add_f32_e32 v134, v135, v134
	ds_bpermute_b32 v135, v131, v134
	s_waitcnt lgkmcnt(0)
	v_add_f32_e32 v134, v134, v135
	ds_bpermute_b32 v135, v130, v134
	s_and_saveexec_b64 s[2:3], vcc
	s_cbranch_execz .LBB0_1594
	s_lshl_b32 s22, s31, 11
	s_add_i32 s22, s14, s22
	v_mul_f32_e32 v136, 0x3c800000, v133
	s_waitcnt lgkmcnt(0)
	v_add_f32_e32 v137, v134, v135
	v_lshl_add_u32 v133, v154, 5, s22
	ds_write_b64 v133, v[136:137]

; #define EPI_ROWS(ai, m) _Pragma("unroll") for (int ai = 0; ai < 2; ++ai) _Pragma("unroll") for (int m = 0; m < 4; ++m)
; #define EPI_COLS(bj, n) _Pragma("unroll") for (int bj = 0; bj < 2; ++bj) _Pragma("unroll") for (int n = 0; n < 2; ++n)
;     __device__ __forceinline__ void fused(Acc& acc, const Unit& u, int wr, int wc, int fr, int fq) const {
;     ...
;         { const float* gp = gate + (size_t)((u.pm * 256) >> 11) * MODW + colb;
;           EPI_COLS(bj, n) gv[bj][n] = *(const f32x4*)(gp + bj * 128 + n * 16); }
;         EPI_ROWS(ai, m) { const int row = u.pm * 256 + ai * 128 + wr * 64 + m * 16 + fr; const float* hp = H + (size_t)row * D + colb;
;             EPI_COLS(bj, n) { const int co = bj * 128 + n * 16; acc[ai][bj][m][n] = *(const f32x4*)(hp + co) * ALPHA + gv[bj][n] * acc[ai][bj][m][n]; }
.LBB0_1669:
	s_waitcnt vmcnt(0)
	s_barrier
	s_lshl_b32 s2, s4, 8
	s_lshl_b32 s3, s31, 5
	s_add_i32 s3, s3, s2
	s_ashr_i32 s2, s30, 3
	s_mul_i32 s46, s2, 0xc000
	s_mul_hi_i32 s24, s2, 0xc000
	s_add_u32 s2, s60, s46
	v_lshl_add_u32 v190, v155, 2, s3
	s_addc_u32 s3, s61, s24
	s_lshl_b32 s38, s30, 8
	v_lshl_add_u32 v0, s5, 6, v154
	v_ashrrev_i32_e32 v191, 31, v190
	v_add_u32_e32 v200, s38, v0
	v_lshlrev_b64 v[178:179], 2, v[190:191]
	v_ashrrev_i32_e32 v201, 31, v200
	v_lshl_add_u64 v[122:123], s[2:3], 0, v[178:179]
	v_lshlrev_b64 v[206:207], 13, v[200:201]
	global_load_dwordx4 v[150:153], v[122:123], off
	global_load_dwordx4 v[146:149], v[122:123], off offset:64
	global_load_dwordx4 v[142:145], v[122:123], off offset:512
	global_load_dwordx4 v[138:141], v[122:123], off offset:576
	v_add_u32_e32 v180, 16, v200
	v_ashrrev_i32_e32 v181, 31, v180
	v_lshlrev_b64 v[182:183], 13, v[180:181]
	v_add_u32_e32 v184, 32, v200
	v_ashrrev_i32_e32 v185, 31, v184
	v_lshlrev_b64 v[186:187], 13, v[184:185]
	v_add_u32_e32 v188, 48, v200
	v_ashrrev_i32_e32 v189, 31, v188
	v_lshlrev_b64 v[198:199], 13, v[188:189]
	v_add_u32_e32 v202, 0x80, v200
	v_ashrrev_i32_e32 v203, 31, v202
	v_lshlrev_b64 v[204:205], 13, v[202:203]
	v_add_u32_e32 v208, 0x90, v200
	v_ashrrev_i32_e32 v209, 31, v208
	v_lshlrev_b64 v[210:211], 13, v[208:209]
	v_add_u32_e32 v212, 0xa0, v200
	v_ashrrev_i32_e32 v213, 31, v212
	v_lshlrev_b64 v[214:215], 13, v[212:213]
	v_add_u32_e32 v216, 0xb0, v200
	v_ashrrev_i32_e32 v217, 31, v216
	v_lshlrev_b64 v[218:219], 13, v[216:217]
	s_lshl_b32 s2, s31, 3
	s_add_i32 s14, s2, 0
	v_cmp_eq_u32_e32 vcc, 0, v155
	s_add_i32 s14, s14, 0x20000
	v_lshl_add_u64 v[196:197], s[70:71], 0, v[206:207]
	v_lshl_add_u64 v[196:197], v[196:197], 0, v[178:179]
	global_load_dwordx4 v[158:161], v[196:197], off
	global_load_dwordx4 v[162:165], v[196:197], off offset:64
	global_load_dwordx4 v[166:169], v[196:197], off offset:512
	global_load_dwordx4 v[170:173], v[196:197], off offset:576
	v_lshl_add_u64 v[196:197], s[70:71], 0, v[182:183]
	v_lshl_add_u64 v[196:197], v[196:197], 0, v[178:179]
	global_load_dwordx4 v[174:177], v[196:197], off
	global_load_dwordx4 v[192:195], v[196:197], off offset:64
	global_load_dwordx4 v[220:223], v[196:197], off offset:512
	global_load_dwordx4 v[224:227], v[196:197], off offset:576
	v_lshl_add_u64 v[196:197], s[70:71], 0, v[186:187]
	v_lshl_add_u64 v[196:197], v[196:197], 0, v[178:179]
	global_load_dwordx4 v[228:231], v[196:197], off
	global_load_dwordx4 v[232:235], v[196:197], off offset:64
	global_load_dwordx4 v[236:239], v[196:197], off offset:512
	global_load_dwordx4 v[240:243], v[196:197], off offset:576
	s_waitcnt vmcnt(8)
	v_pk_mul_f32 v[124:125], v[160:161], s[84:85] op_sel_hi:[1,0]
	v_pk_mul_f32 v[122:123], v[158:159], s[84:85] op_sel_hi:[1,0]
	v_pk_fma_f32 v[64:65], v[64:65], v[152:153], v[124:125]
	v_pk_fma_f32 v[62:63], v[62:63], v[150:151], v[122:123]
	v_pk_mul_f32 v[124:125], v[164:165], s[84:85] op_sel_hi:[1,0]
	v_pk_mul_f32 v[122:123], v[162:163], s[84:85] op_sel_hi:[1,0]
	v_pk_fma_f32 v[44:45], v[44:45], v[148:149], v[124:125]
	v_pk_fma_f32 v[42:43], v[42:43], v[146:147], v[122:123]
	v_pk_mul_f32 v[124:125], v[168:169], s[84:85] op_sel_hi:[1,0]
	v_pk_mul_f32 v[122:123], v[166:167], s[84:85] op_sel_hi:[1,0]
	v_pk_fma_f32 v[36:37], v[36:37], v[144:145], v[124:125]
	v_pk_fma_f32 v[34:35], v[34:35], v[142:143], v[122:123]
	v_pk_mul_f32 v[122:123], v[170:171], s[84:85] op_sel_hi:[1,0]
	v_pk_mul_f32 v[124:125], v[172:173], s[84:85] op_sel_hi:[1,0]
	v_lshl_add_u64 v[196:197], s[70:71], 0, v[198:199]
	v_lshl_add_u64 v[196:197], v[196:197], 0, v[178:179]
	global_load_dwordx4 v[158:161], v[196:197], off
	global_load_dwordx4 v[162:165], v[196:197], off offset:64
	global_load_dwordx4 v[166:169], v[196:197], off offset:512
	global_load_dwordx4 v[170:173], v[196:197], off offset:576
	v_pk_fma_f32 v[2:3], v[2:3], v[138:139], v[122:123]
	v_pk_fma_f32 v[4:5], v[4:5], v[140:141], v[124:125]
	s_waitcnt vmcnt(8)
	v_pk_mul_f32 v[124:125], v[176:177], s[84:85] op_sel_hi:[1,0]
	v_pk_mul_f32 v[122:123], v[174:175], s[84:85] op_sel_hi:[1,0]
	v_pk_fma_f32 v[20:21], v[20:21], v[152:153], v[124:125]
	v_pk_fma_f32 v[18:19], v[18:19], v[150:151], v[122:123]
	v_pk_mul_f32 v[124:125], v[194:195], s[84:85] op_sel_hi:[1,0]
	v_pk_mul_f32 v[122:123], v[192:193], s[84:85] op_sel_hi:[1,0]
	v_pk_fma_f32 v[16:17], v[16:17], v[148:149], v[124:125]
	v_pk_fma_f32 v[14:15], v[14:15], v[146:147], v[122:123]
	v_pk_mul_f32 v[124:125], v[222:223], s[84:85] op_sel_hi:[1,0]
	v_pk_mul_f32 v[122:123], v[220:221], s[84:85] op_sel_hi:[1,0]
	v_pk_fma_f32 v[12:13], v[12:13], v[144:145], v[124:125]
	v_pk_fma_f32 v[10:11], v[10:11], v[142:143], v[122:123]
	v_pk_mul_f32 v[122:123], v[224:225], s[84:85] op_sel_hi:[1,0]
	v_pk_mul_f32 v[124:125], v[226:227], s[84:85] op_sel_hi:[1,0]
	v_lshl_add_u64 v[196:197], s[70:71], 0, v[204:205]
	v_lshl_add_u64 v[196:197], v[196:197], 0, v[178:179]
	global_load_dwordx4 v[174:177], v[196:197], off
	global_load_dwordx4 v[192:195], v[196:197], off offset:64
	global_load_dwordx4 v[220:223], v[196:197], off offset:512
	global_load_dwordx4 v[224:227], v[196:197], off offset:576
	v_pk_fma_f32 v[6:7], v[6:7], v[138:139], v[122:123]
	v_pk_fma_f32 v[8:9], v[8:9], v[140:141], v[124:125]
	s_waitcnt vmcnt(8)
; #define EPI_ROWS(ai, m) _Pragma("unroll") for (int ai = 0; ai < 2; ++ai) _Pragma("unroll") for (int m = 0; m < 4; ++m)
; #define EPI_COLS(bj, n) _Pragma("unroll") for (int bj = 0; bj < 2; ++bj) _Pragma("unroll") for (int n = 0; n < 2; ++n)
;     __device__ __forceinline__ void fused(Acc& acc, const Unit& u, int wr, int wc, int fr, int fq) const {
;     ...
;         EPI_ROWS(ai, m) { const int row = u.pm * 256 + ai * 128 + wr * 64 + m * 16 + fr; const float* hp = H + (size_t)row * D + colb;
;             EPI_COLS(bj, n) { const int co = bj * 128 + n * 16; acc[ai][bj][m][n] = *(const f32x4*)(hp + co) * ALPHA + gv[bj][n] * acc[ai][bj][m][n]; }
	v_pk_mul_f32 v[124:125], v[230:231], s[84:85] op_sel_hi:[1,0]
	v_pk_mul_f32 v[122:123], v[228:229], s[84:85] op_sel_hi:[1,0]
	v_pk_fma_f32 v[40:41], v[40:41], v[152:153], v[124:125]
	v_pk_fma_f32 v[38:39], v[38:39], v[150:151], v[122:123]
	v_pk_mul_f32 v[124:125], v[234:235], s[84:85] op_sel_hi:[1,0]
	v_pk_mul_f32 v[122:123], v[232:233], s[84:85] op_sel_hi:[1,0]
	v_pk_fma_f32 v[32:33], v[32:33], v[148:149], v[124:125]
	v_pk_fma_f32 v[30:31], v[30:31], v[146:147], v[122:123]
	v_pk_mul_f32 v[124:125], v[238:239], s[84:85] op_sel_hi:[1,0]
	v_pk_mul_f32 v[122:123], v[236:237], s[84:85] op_sel_hi:[1,0]
	v_pk_fma_f32 v[28:29], v[28:29], v[144:145], v[124:125]
	v_pk_fma_f32 v[26:27], v[26:27], v[142:143], v[122:123]
	v_pk_mul_f32 v[122:123], v[240:241], s[84:85] op_sel_hi:[1,0]
	v_pk_mul_f32 v[124:125], v[242:243], s[84:85] op_sel_hi:[1,0]
	v_lshl_add_u64 v[196:197], s[70:71], 0, v[210:211]
	v_lshl_add_u64 v[196:197], v[196:197], 0, v[178:179]
	global_load_dwordx4 v[228:231], v[196:197], off
	global_load_dwordx4 v[232:235], v[196:197], off offset:64
	global_load_dwordx4 v[236:239], v[196:197], off offset:512
	global_load_dwordx4 v[240:243], v[196:197], off offset:576
	v_pk_fma_f32 v[22:23], v[22:23], v[138:139], v[122:123]
	v_pk_fma_f32 v[24:25], v[24:25], v[140:141], v[124:125]
	s_waitcnt vmcnt(8)
	v_pk_mul_f32 v[124:125], v[160:161], s[84:85] op_sel_hi:[1,0]
	v_pk_mul_f32 v[122:123], v[158:159], s[84:85] op_sel_hi:[1,0]
	v_pk_fma_f32 v[60:61], v[60:61], v[152:153], v[124:125]
	v_pk_fma_f32 v[58:59], v[58:59], v[150:151], v[122:123]
	v_pk_mul_f32 v[124:125], v[164:165], s[84:85] op_sel_hi:[1,0]
	v_pk_mul_f32 v[122:123], v[162:163], s[84:85] op_sel_hi:[1,0]
	v_pk_fma_f32 v[56:57], v[56:57], v[148:149], v[124:125]
	v_pk_fma_f32 v[54:55], v[54:55], v[146:147], v[122:123]
	v_pk_mul_f32 v[124:125], v[168:169], s[84:85] op_sel_hi:[1,0]
	v_pk_mul_f32 v[122:123], v[166:167], s[84:85] op_sel_hi:[1,0]
	v_pk_fma_f32 v[52:53], v[52:53], v[144:145], v[124:125]
	v_pk_fma_f32 v[50:51], v[50:51], v[142:143], v[122:123]
	v_pk_mul_f32 v[124:125], v[172:173], s[84:85] op_sel_hi:[1,0]
	v_pk_mul_f32 v[122:123], v[170:171], s[84:85] op_sel_hi:[1,0]
	v_lshl_add_u64 v[196:197], s[70:71], 0, v[214:215]
	v_lshl_add_u64 v[196:197], v[196:197], 0, v[178:179]
	global_load_dwordx4 v[158:161], v[196:197], off
	global_load_dwordx4 v[162:165], v[196:197], off offset:64
	global_load_dwordx4 v[166:169], v[196:197], off offset:512
	global_load_dwordx4 v[170:173], v[196:197], off offset:576
	v_pk_fma_f32 v[48:49], v[48:49], v[140:141], v[124:125]
	v_pk_fma_f32 v[46:47], v[46:47], v[138:139], v[122:123]
	s_waitcnt vmcnt(8)
	v_pk_mul_f32 v[124:125], v[176:177], s[84:85] op_sel_hi:[1,0]
	v_pk_mul_f32 v[122:123], v[174:175], s[84:85] op_sel_hi:[1,0]
	v_pk_fma_f32 v[80:81], v[80:81], v[152:153], v[124:125]
	v_pk_fma_f32 v[78:79], v[78:79], v[150:151], v[122:123]
	v_pk_mul_f32 v[124:125], v[194:195], s[84:85] op_sel_hi:[1,0]
	v_pk_mul_f32 v[122:123], v[192:193], s[84:85] op_sel_hi:[1,0]
	v_pk_fma_f32 v[76:77], v[76:77], v[148:149], v[124:125]
	v_pk_fma_f32 v[74:75], v[74:75], v[146:147], v[122:123]
	v_pk_mul_f32 v[124:125], v[222:223], s[84:85] op_sel_hi:[1,0]
	v_pk_mul_f32 v[122:123], v[220:221], s[84:85] op_sel_hi:[1,0]
	v_pk_fma_f32 v[72:73], v[72:73], v[144:145], v[124:125]
	v_pk_fma_f32 v[70:71], v[70:71], v[142:143], v[122:123]
	v_pk_mul_f32 v[122:123], v[224:225], s[84:85] op_sel_hi:[1,0]
	v_pk_mul_f32 v[124:125], v[226:227], s[84:85] op_sel_hi:[1,0]
	v_lshl_add_u64 v[196:197], s[70:71], 0, v[218:219]
	v_lshl_add_u64 v[196:197], v[196:197], 0, v[178:179]
	global_load_dwordx4 v[174:177], v[196:197], off
	global_load_dwordx4 v[192:195], v[196:197], off offset:64
	global_load_dwordx4 v[220:223], v[196:197], off offset:512
	global_load_dwordx4 v[224:227], v[196:197], off offset:576
	v_pk_fma_f32 v[66:67], v[66:67], v[138:139], v[122:123]
	v_pk_fma_f32 v[68:69], v[68:69], v[140:141], v[124:125]
	s_waitcnt vmcnt(8)
	v_pk_mul_f32 v[124:125], v[230:231], s[84:85] op_sel_hi:[1,0]
	v_pk_mul_f32 v[122:123], v[228:229], s[84:85] op_sel_hi:[1,0]
	v_pk_fma_f32 v[100:101], v[100:101], v[152:153], v[124:125]
	v_pk_fma_f32 v[98:99], v[98:99], v[150:151], v[122:123]
	v_pk_mul_f32 v[124:125], v[234:235], s[84:85] op_sel_hi:[1,0]
	v_pk_mul_f32 v[122:123], v[232:233], s[84:85] op_sel_hi:[1,0]
	v_pk_fma_f32 v[96:97], v[96:97], v[148:149], v[124:125]
	v_pk_fma_f32 v[94:95], v[94:95], v[146:147], v[122:123]
	v_pk_mul_f32 v[124:125], v[238:239], s[84:85] op_sel_hi:[1,0]
	v_pk_mul_f32 v[122:123], v[236:237], s[84:85] op_sel_hi:[1,0]
	v_pk_fma_f32 v[92:93], v[92:93], v[144:145], v[124:125]
	v_pk_fma_f32 v[90:91], v[90:91], v[142:143], v[122:123]
	v_pk_mul_f32 v[122:123], v[240:241], s[84:85] op_sel_hi:[1,0]
	v_pk_mul_f32 v[124:125], v[242:243], s[84:85] op_sel_hi:[1,0]
	v_pk_fma_f32 v[86:87], v[86:87], v[138:139], v[122:123]
	v_pk_fma_f32 v[88:89], v[88:89], v[140:141], v[124:125]
	s_waitcnt vmcnt(4)
; __device__ __forceinline__ float shx(float v, int mask, int lane) { return __int_as_float(__builtin_amdgcn_ds_bpermute((lane ^ mask) << 2, __float_as_int(v))); }
; #define EPI_ROWS(ai, m) _Pragma("unroll") for (int ai = 0; ai < 2; ++ai) _Pragma("unroll") for (int m = 0; m < 4; ++m)
; #define EPI_COLS(bj, n) _Pragma("unroll") for (int bj = 0; bj < 2; ++bj) _Pragma("unroll") for (int n = 0; n < 2; ++n)
;     __device__ __forceinline__ void run(const Acc& v, const Unit& u, int wr, int wc, int fr, int fq, LAS unsigned char* sl, int wid, int lane) const {
;     ...
;                 float sm = 0.f;
; #pragma unroll
;                 for (int bj = 0; bj < 2; ++bj)
; #pragma unroll
;                     for (int n = 0; n < 2; ++n) { const f32x4 x = v[ai][bj][m][n]; sm += (x[0] + x[1]) + (x[2] + x[3]); }
;                 sm += shx(sm, 16, lane); sm += shx(sm, 32, lane);
;                 const float mw = sm * (1.0f / 64.0f); float q = 0.f;
; #pragma unroll
;                 for (int bj = 0; bj < 2; ++bj)
; #pragma unroll
;                     for (int n = 0; n < 2; ++n) { const f32x4 d = v[ai][bj][m][n] - mw; q += (d[0] * d[0] + d[1] * d[1]) + (d[2] * d[2] + d[3] * d[3]); }
;                 q += shx(q, 16, lane); q += shx(q, 32, lane);
;                 if (fq == 0) P[(ai * 128 + wr * 64 + m * 16 + fr) * 4 + wc] = (f32x2){mw, q};
;     __device__ __forceinline__ void fused(Acc& acc, const Unit& u, int wr, int wc, int fr, int fq) const {
;     ...
;         EPI_ROWS(ai, m) { const int row = u.pm * 256 + ai * 128 + wr * 64 + m * 16 + fr; const float* hp = H + (size_t)row * D + colb;
;             EPI_COLS(bj, n) { const int co = bj * 128 + n * 16; acc[ai][bj][m][n] = *(const f32x4*)(hp + co) * ALPHA + gv[bj][n] * acc[ai][bj][m][n]; }
	v_pk_mul_f32 v[124:125], v[160:161], s[84:85] op_sel_hi:[1,0]
	v_pk_mul_f32 v[122:123], v[158:159], s[84:85] op_sel_hi:[1,0]
	v_pk_fma_f32 v[128:129], v[120:121], v[152:153], v[124:125]
	v_pk_fma_f32 v[126:127], v[118:119], v[150:151], v[122:123]
	v_pk_mul_f32 v[120:121], v[164:165], s[84:85] op_sel_hi:[1,0]
	v_pk_mul_f32 v[118:119], v[162:163], s[84:85] op_sel_hi:[1,0]
	v_pk_fma_f32 v[124:125], v[116:117], v[148:149], v[120:121]
	v_pk_fma_f32 v[122:123], v[114:115], v[146:147], v[118:119]
	v_pk_mul_f32 v[116:117], v[168:169], s[84:85] op_sel_hi:[1,0]
	v_pk_mul_f32 v[114:115], v[166:167], s[84:85] op_sel_hi:[1,0]
	v_pk_fma_f32 v[120:121], v[112:113], v[144:145], v[116:117]
	v_pk_fma_f32 v[118:119], v[110:111], v[142:143], v[114:115]
	v_pk_mul_f32 v[110:111], v[170:171], s[84:85] op_sel_hi:[1,0]
	v_pk_mul_f32 v[112:113], v[172:173], s[84:85] op_sel_hi:[1,0]
	v_pk_fma_f32 v[114:115], v[106:107], v[138:139], v[110:111]
	v_pk_fma_f32 v[116:117], v[108:109], v[140:141], v[112:113]
	s_waitcnt vmcnt(0)
	v_pk_mul_f32 v[108:109], v[176:177], s[84:85] op_sel_hi:[1,0]
	v_pk_mul_f32 v[106:107], v[174:175], s[84:85] op_sel_hi:[1,0]
	v_pk_fma_f32 v[112:113], v[136:137], v[152:153], v[108:109]
	v_pk_fma_f32 v[110:111], v[134:135], v[150:151], v[106:107]
	v_mov_b32_e32 v134, v63
	v_mov_b32_e32 v135, v64
	v_mov_b32_e32 v136, v62
	v_mov_b32_e32 v137, v65
	v_pk_add_f32 v[134:135], v[134:135], v[136:137]
	v_mov_b32_e32 v136, v43
	v_mov_b32_e32 v137, v44
	v_pk_mul_f32 v[108:109], v[194:195], s[84:85] op_sel_hi:[1,0]
	v_pk_mul_f32 v[106:107], v[192:193], s[84:85] op_sel_hi:[1,0]
	v_pk_fma_f32 v[108:109], v[132:133], v[148:149], v[108:109]
	v_pk_fma_f32 v[106:107], v[130:131], v[146:147], v[106:107]
	v_pk_mul_f32 v[132:133], v[222:223], s[84:85] op_sel_hi:[1,0]
	v_pk_mul_f32 v[130:131], v[220:221], s[84:85] op_sel_hi:[1,0]
	v_pk_fma_f32 v[104:105], v[104:105], v[144:145], v[132:133]
	v_pk_fma_f32 v[102:103], v[102:103], v[142:143], v[130:131]
	v_pk_mul_f32 v[130:131], v[224:225], s[84:85] op_sel_hi:[1,0]
	s_nop 0
	v_pk_fma_f32 v[82:83], v[82:83], v[138:139], v[130:131]
	v_mov_b32_e32 v138, v42
	v_mov_b32_e32 v139, v45
	v_pk_mul_f32 v[132:133], v[226:227], s[84:85] op_sel_hi:[1,0]
	v_pk_add_f32 v[136:137], v[136:137], v[138:139]
	v_pk_fma_f32 v[84:85], v[84:85], v[140:141], v[132:133]
	v_add_f32_e32 v133, v134, v135
	v_pk_add_f32 v[136:137], v[136:137], v[136:137] op_sel_hi:[0,1]
	v_add_f32_e32 v135, 0, v133
	v_add_f32_e32 v139, v34, v35
	v_add_f32_e32 v141, v36, v37
	v_mov_b32_e32 v138, v2
	v_mov_b32_e32 v140, v3
	v_mov_b32_e32 v136, v4
	v_mov_b32_e32 v134, v5
	v_lshl_add_u32 v132, v155, 4, v154
	v_pk_add_f32 v[138:139], v[138:139], v[140:141]
	v_pk_add_f32 v[134:135], v[136:137], v[134:135]
	v_lshlrev_b32_e32 v130, 2, v132
	v_pk_add_f32 v[134:135], v[138:139], v[134:135]
	v_xor_b32_e32 v131, 64, v130
	v_add_f32_e32 v133, v134, v135
	ds_bpermute_b32 v134, v131, v133
	v_xor_b32_e32 v130, 0x80, v130
	s_waitcnt lgkmcnt(0)
	v_add_f32_e32 v133, v133, v134
	ds_bpermute_b32 v134, v130, v133
	s_waitcnt lgkmcnt(0)
	v_add_f32_e32 v133, v133, v134
	v_fmamk_f32 v135, v133, 0xbc800000, v65
	v_fmamk_f32 v137, v133, 0xbc800000, v63
	v_fmamk_f32 v134, v133, 0xbc800000, v64
	v_fmamk_f32 v136, v133, 0xbc800000, v62
	v_mul_f32_e32 v137, v137, v137
	v_mul_f32_e32 v135, v135, v135
	v_fmac_f32_e32 v137, v136, v136
	v_fmac_f32_e32 v135, v134, v134
	v_fmamk_f32 v136, v133, 0xbc800000, v45
	v_fmamk_f32 v138, v133, 0xbc800000, v43
	v_add_f32_e32 v134, v137, v135
	v_fmamk_f32 v135, v133, 0xbc800000, v44
	v_fmamk_f32 v137, v133, 0xbc800000, v42
	v_mul_f32_e32 v138, v138, v138
	v_mul_f32_e32 v136, v136, v136
	v_fmac_f32_e32 v138, v137, v137
	v_fmac_f32_e32 v136, v135, v135
	v_add_f32_e32 v135, v138, v136
	v_fmamk_f32 v136, v133, 0xbc800000, v37
	v_fmamk_f32 v138, v133, 0xbc800000, v35
	v_add_f32_e32 v134, v134, v135
	v_fmamk_f32 v135, v133, 0xbc800000, v36
	v_fmamk_f32 v137, v133, 0xbc800000, v34
	v_mul_f32_e32 v138, v138, v138
	v_mul_f32_e32 v136, v136, v136
	v_fmac_f32_e32 v138, v137, v137
	v_fmac_f32_e32 v136, v135, v135
	v_add_f32_e32 v135, v138, v136
	v_fmamk_f32 v136, v133, 0xbc800000, v5
	v_fmamk_f32 v138, v133, 0xbc800000, v3
	v_add_f32_e32 v134, v135, v134
	v_fmamk_f32 v135, v133, 0xbc800000, v4
	v_fmamk_f32 v137, v133, 0xbc800000, v2
	v_mul_f32_e32 v138, v138, v138
	v_mul_f32_e32 v136, v136, v136
	v_fmac_f32_e32 v138, v137, v137
	v_fmac_f32_e32 v136, v135, v135
	v_add_f32_e32 v135, v138, v136
	v_add_f32_e32 v134, v135, v134
	ds_bpermute_b32 v135, v131, v134
	s_waitcnt lgkmcnt(0)
	v_add_f32_e32 v134, v134, v135
	ds_bpermute_b32 v135, v130, v134
	s_and_saveexec_b64 s[2:3], vcc
	s_cbranch_execz .LBB0_1671
	s_lshl_b32 s22, s5, 11
	s_add_i32 s22, s14, s22
	v_mul_f32_e32 v136, 0x3c800000, v133
	s_waitcnt lgkmcnt(0)
	v_add_f32_e32 v137, v134, v135
	v_lshl_add_u32 v133, v154, 5, s22
	ds_write_b64 v133, v[136:137]

; #define EPI_ROWS(ai, m) _Pragma("unroll") for (int ai = 0; ai < 2; ++ai) _Pragma("unroll") for (int m = 0; m < 4; ++m)
; #define EPI_COLS(bj, n) _Pragma("unroll") for (int bj = 0; bj < 2; ++bj) _Pragma("unroll") for (int n = 0; n < 2; ++n)
;     __device__ __forceinline__ void fused(Acc& acc, const Unit& u, int wr, int wc, int fr, int fq) const {
;     ...
;         { const float* gp = gate + (size_t)((u.pm * 256) >> 11) * MODW + colb;
;           EPI_COLS(bj, n) gv[bj][n] = *(const f32x4*)(gp + bj * 128 + n * 16); }
;         EPI_ROWS(ai, m) { const int row = u.pm * 256 + ai * 128 + wr * 64 + m * 16 + fr; const float* hp = H + (size_t)row * D + colb;
;             EPI_COLS(bj, n) { const int co = bj * 128 + n * 16; acc[ai][bj][m][n] = *(const f32x4*)(hp + co) * ALPHA + gv[bj][n] * acc[ai][bj][m][n]; }
.LBB0_1861:
	v_readlane_b32 s16, v255, 44
	s_mul_i32 s14, s16, 0x3c000
	s_add_u32 s14, s8, s14
	s_mul_hi_u32 s16, s16, 0x3c000
	s_addc_u32 s16, s9, s16
	s_add_u32 s51, s14, 0x100000
	s_addc_u32 s52, s16, 0
	s_waitcnt vmcnt(0)
	s_barrier
	s_lshl_b32 s14, s4, 8
	s_lshl_b32 s16, s59, 5
	s_add_i32 s16, s16, s14
	s_ashr_i32 s14, s58, 3
	v_lshl_add_u32 v178, v157, 2, s16
	s_mul_i32 s50, s14, 0xc000
	v_readlane_b32 s17, v255, 45
	s_mul_hi_i32 s24, s14, 0xc000
	s_add_u32 s16, s51, s50
	v_ashrrev_i32_e32 v179, 31, v178
	s_addc_u32 s17, s52, s24
	v_lshlrev_b64 v[154:155], 2, v[178:179]
	s_lshl_b32 s40, s58, 8
	v_lshl_add_u32 v0, s5, 6, v156
	v_lshl_add_u64 v[122:123], s[16:17], 0, v[154:155]
	s_mov_b64 s[16:17], 0xa000
	s_mov_b32 s95, 0xa000
	v_add_u32_e32 v214, s40, v0
	v_lshl_add_u64 v[124:125], v[122:123], 0, s[16:17]
	v_add_co_u32_e32 v122, vcc, s95, v122
	v_ashrrev_i32_e32 v215, 31, v214
	s_nop 0
	v_addc_co_u32_e32 v123, vcc, 0, v123, vcc
	v_lshlrev_b64 v[216:217], 13, v[214:215]
	global_load_dwordx4 v[150:153], v[122:123], off
	global_load_dwordx4 v[146:149], v[124:125], off offset:64
	global_load_dwordx4 v[142:145], v[124:125], off offset:512
	global_load_dwordx4 v[138:141], v[124:125], off offset:576
	v_add_u32_e32 v208, 16, v214
	v_ashrrev_i32_e32 v209, 31, v208
	v_lshlrev_b64 v[212:213], 13, v[208:209]
	v_add_u32_e32 v204, 32, v214
	v_ashrrev_i32_e32 v205, 31, v204
	v_lshlrev_b64 v[210:211], 13, v[204:205]
	v_add_u32_e32 v200, 48, v214
	v_ashrrev_i32_e32 v201, 31, v200
	v_lshlrev_b64 v[206:207], 13, v[200:201]
	v_add_u32_e32 v190, 0x80, v214
	v_ashrrev_i32_e32 v191, 31, v190
	v_lshlrev_b64 v[202:203], 13, v[190:191]
	v_add_u32_e32 v186, 0x90, v214
	v_ashrrev_i32_e32 v187, 31, v186
	v_lshlrev_b64 v[198:199], 13, v[186:187]
	v_add_u32_e32 v184, 0xa0, v214
	v_ashrrev_i32_e32 v185, 31, v184
	v_lshlrev_b64 v[188:189], 13, v[184:185]
	v_add_u32_e32 v180, 0xb0, v214
	v_ashrrev_i32_e32 v181, 31, v180
	v_lshlrev_b64 v[182:183], 13, v[180:181]
	v_cmp_eq_u32_e32 vcc, 0, v157
	v_lshl_add_u64 v[176:177], s[2:3], 0, v[216:217]
	v_lshl_add_u64 v[176:177], v[176:177], 0, v[154:155]
	global_load_dwordx4 v[160:163], v[176:177], off
	global_load_dwordx4 v[164:167], v[176:177], off offset:64
	global_load_dwordx4 v[168:171], v[176:177], off offset:512
	global_load_dwordx4 v[172:175], v[176:177], off offset:576
	v_lshl_add_u64 v[176:177], s[2:3], 0, v[212:213]
	v_lshl_add_u64 v[176:177], v[176:177], 0, v[154:155]
	global_load_dwordx4 v[192:195], v[176:177], off
	global_load_dwordx4 v[218:221], v[176:177], off offset:64
	global_load_dwordx4 v[222:225], v[176:177], off offset:512
	global_load_dwordx4 v[226:229], v[176:177], off offset:576
	s_waitcnt vmcnt(4)
	v_pk_mul_f32 v[124:125], v[162:163], s[84:85] op_sel_hi:[1,0]
	v_pk_mul_f32 v[122:123], v[160:161], s[84:85] op_sel_hi:[1,0]
	v_pk_fma_f32 v[124:125], v[120:121], v[152:153], v[124:125]
	v_pk_fma_f32 v[122:123], v[118:119], v[150:151], v[122:123]
	v_pk_mul_f32 v[120:121], v[166:167], s[84:85] op_sel_hi:[1,0]
	v_pk_mul_f32 v[118:119], v[164:165], s[84:85] op_sel_hi:[1,0]
	v_pk_fma_f32 v[128:129], v[116:117], v[148:149], v[120:121]
	v_pk_fma_f32 v[126:127], v[114:115], v[146:147], v[118:119]
	v_pk_mul_f32 v[116:117], v[170:171], s[84:85] op_sel_hi:[1,0]
	v_pk_mul_f32 v[114:115], v[168:169], s[84:85] op_sel_hi:[1,0]
	v_pk_fma_f32 v[100:101], v[100:101], v[144:145], v[116:117]
	v_pk_fma_f32 v[98:99], v[98:99], v[142:143], v[114:115]
	v_pk_mul_f32 v[114:115], v[172:173], s[84:85] op_sel_hi:[1,0]
	v_pk_mul_f32 v[116:117], v[174:175], s[84:85] op_sel_hi:[1,0]
	v_lshl_add_u64 v[176:177], s[2:3], 0, v[210:211]
	v_lshl_add_u64 v[176:177], v[176:177], 0, v[154:155]
	global_load_dwordx4 v[160:163], v[176:177], off
	global_load_dwordx4 v[164:167], v[176:177], off offset:64
	global_load_dwordx4 v[168:171], v[176:177], off offset:512
	global_load_dwordx4 v[172:175], v[176:177], off offset:576
	v_pk_fma_f32 v[102:103], v[102:103], v[138:139], v[114:115]
	v_pk_fma_f32 v[104:105], v[104:105], v[140:141], v[116:117]
	s_waitcnt vmcnt(4)
	v_pk_mul_f32 v[116:117], v[194:195], s[84:85] op_sel_hi:[1,0]
	v_pk_mul_f32 v[114:115], v[192:193], s[84:85] op_sel_hi:[1,0]
	v_pk_fma_f32 v[116:117], v[112:113], v[152:153], v[116:117]
	v_pk_fma_f32 v[114:115], v[110:111], v[150:151], v[114:115]
	v_pk_mul_f32 v[112:113], v[220:221], s[84:85] op_sel_hi:[1,0]
	v_pk_mul_f32 v[110:111], v[218:219], s[84:85] op_sel_hi:[1,0]
	v_pk_fma_f32 v[120:121], v[108:109], v[148:149], v[112:113]
	v_pk_fma_f32 v[118:119], v[106:107], v[146:147], v[110:111]
	v_pk_mul_f32 v[108:109], v[224:225], s[84:85] op_sel_hi:[1,0]
	v_pk_mul_f32 v[106:107], v[222:223], s[84:85] op_sel_hi:[1,0]
	v_pk_fma_f32 v[92:93], v[92:93], v[144:145], v[108:109]
	v_pk_fma_f32 v[90:91], v[90:91], v[142:143], v[106:107]
	v_pk_mul_f32 v[106:107], v[226:227], s[84:85] op_sel_hi:[1,0]
	v_pk_mul_f32 v[108:109], v[228:229], s[84:85] op_sel_hi:[1,0]
	v_lshl_add_u64 v[176:177], s[2:3], 0, v[206:207]
	v_lshl_add_u64 v[176:177], v[176:177], 0, v[154:155]
	global_load_dwordx4 v[192:195], v[176:177], off
	global_load_dwordx4 v[218:221], v[176:177], off offset:64
	global_load_dwordx4 v[222:225], v[176:177], off offset:512
	global_load_dwordx4 v[226:229], v[176:177], off offset:576
	v_pk_fma_f32 v[94:95], v[94:95], v[138:139], v[106:107]
	v_pk_fma_f32 v[96:97], v[96:97], v[140:141], v[108:109]
	s_waitcnt vmcnt(4)
; #define EPI_ROWS(ai, m) _Pragma("unroll") for (int ai = 0; ai < 2; ++ai) _Pragma("unroll") for (int m = 0; m < 4; ++m)
; #define EPI_COLS(bj, n) _Pragma("unroll") for (int bj = 0; bj < 2; ++bj) _Pragma("unroll") for (int n = 0; n < 2; ++n)
;     __device__ __forceinline__ void fused(Acc& acc, const Unit& u, int wr, int wc, int fr, int fq) const {
;     ...
;         EPI_ROWS(ai, m) { const int row = u.pm * 256 + ai * 128 + wr * 64 + m * 16 + fr; const float* hp = H + (size_t)row * D + colb;
;             EPI_COLS(bj, n) { const int co = bj * 128 + n * 16; acc[ai][bj][m][n] = *(const f32x4*)(hp + co) * ALPHA + gv[bj][n] * acc[ai][bj][m][n]; }
	v_pk_mul_f32 v[108:109], v[162:163], s[84:85] op_sel_hi:[1,0]
	v_pk_mul_f32 v[106:107], v[160:161], s[84:85] op_sel_hi:[1,0]
	v_pk_fma_f32 v[108:109], v[88:89], v[152:153], v[108:109]
	v_pk_fma_f32 v[106:107], v[86:87], v[150:151], v[106:107]
	v_pk_mul_f32 v[88:89], v[166:167], s[84:85] op_sel_hi:[1,0]
	v_pk_mul_f32 v[86:87], v[164:165], s[84:85] op_sel_hi:[1,0]
	v_pk_fma_f32 v[112:113], v[84:85], v[148:149], v[88:89]
	v_pk_fma_f32 v[110:111], v[82:83], v[146:147], v[86:87]
	v_pk_mul_f32 v[84:85], v[170:171], s[84:85] op_sel_hi:[1,0]
	v_pk_mul_f32 v[82:83], v[168:169], s[84:85] op_sel_hi:[1,0]
	v_pk_fma_f32 v[68:69], v[68:69], v[144:145], v[84:85]
	v_pk_fma_f32 v[66:67], v[66:67], v[142:143], v[82:83]
	v_pk_mul_f32 v[82:83], v[172:173], s[84:85] op_sel_hi:[1,0]
	v_pk_mul_f32 v[84:85], v[174:175], s[84:85] op_sel_hi:[1,0]
	v_lshl_add_u64 v[176:177], s[2:3], 0, v[202:203]
	v_lshl_add_u64 v[176:177], v[176:177], 0, v[154:155]
	global_load_dwordx4 v[160:163], v[176:177], off
	global_load_dwordx4 v[164:167], v[176:177], off offset:64
	global_load_dwordx4 v[168:171], v[176:177], off offset:512
	global_load_dwordx4 v[172:175], v[176:177], off offset:576
	v_pk_fma_f32 v[70:71], v[70:71], v[138:139], v[82:83]
	v_pk_fma_f32 v[72:73], v[72:73], v[140:141], v[84:85]
	s_waitcnt vmcnt(4)
	v_pk_mul_f32 v[84:85], v[194:195], s[84:85] op_sel_hi:[1,0]
	v_pk_mul_f32 v[82:83], v[192:193], s[84:85] op_sel_hi:[1,0]
	v_pk_fma_f32 v[84:85], v[80:81], v[152:153], v[84:85]
	v_pk_fma_f32 v[82:83], v[78:79], v[150:151], v[82:83]
	v_pk_mul_f32 v[80:81], v[220:221], s[84:85] op_sel_hi:[1,0]
	v_pk_mul_f32 v[78:79], v[218:219], s[84:85] op_sel_hi:[1,0]
	v_pk_fma_f32 v[88:89], v[76:77], v[148:149], v[80:81]
	v_pk_fma_f32 v[86:87], v[74:75], v[146:147], v[78:79]
	v_pk_mul_f32 v[76:77], v[224:225], s[84:85] op_sel_hi:[1,0]
	v_pk_mul_f32 v[74:75], v[222:223], s[84:85] op_sel_hi:[1,0]
	v_pk_fma_f32 v[52:53], v[52:53], v[144:145], v[76:77]
	v_pk_fma_f32 v[50:51], v[50:51], v[142:143], v[74:75]
	v_pk_mul_f32 v[76:77], v[228:229], s[84:85] op_sel_hi:[1,0]
	v_pk_mul_f32 v[74:75], v[226:227], s[84:85] op_sel_hi:[1,0]
	v_lshl_add_u64 v[176:177], s[2:3], 0, v[198:199]
	v_lshl_add_u64 v[176:177], v[176:177], 0, v[154:155]
	global_load_dwordx4 v[192:195], v[176:177], off
	global_load_dwordx4 v[218:221], v[176:177], off offset:64
	global_load_dwordx4 v[222:225], v[176:177], off offset:512
	global_load_dwordx4 v[226:229], v[176:177], off offset:576
	v_pk_fma_f32 v[56:57], v[56:57], v[140:141], v[76:77]
	v_pk_fma_f32 v[54:55], v[54:55], v[138:139], v[74:75]
	s_waitcnt vmcnt(4)
	v_pk_mul_f32 v[76:77], v[162:163], s[84:85] op_sel_hi:[1,0]
	v_pk_mul_f32 v[74:75], v[160:161], s[84:85] op_sel_hi:[1,0]
	v_pk_fma_f32 v[76:77], v[64:65], v[152:153], v[76:77]
	v_pk_fma_f32 v[74:75], v[62:63], v[150:151], v[74:75]
	v_pk_mul_f32 v[64:65], v[166:167], s[84:85] op_sel_hi:[1,0]
	v_pk_mul_f32 v[62:63], v[164:165], s[84:85] op_sel_hi:[1,0]
	v_pk_fma_f32 v[80:81], v[60:61], v[148:149], v[64:65]
	v_pk_fma_f32 v[78:79], v[58:59], v[146:147], v[62:63]
	v_pk_mul_f32 v[60:61], v[170:171], s[84:85] op_sel_hi:[1,0]
	v_pk_mul_f32 v[58:59], v[168:169], s[84:85] op_sel_hi:[1,0]
	v_pk_fma_f32 v[44:45], v[44:45], v[144:145], v[60:61]
	v_pk_fma_f32 v[42:43], v[42:43], v[142:143], v[58:59]
	v_pk_mul_f32 v[58:59], v[172:173], s[84:85] op_sel_hi:[1,0]
	v_pk_mul_f32 v[60:61], v[174:175], s[84:85] op_sel_hi:[1,0]
	v_lshl_add_u64 v[176:177], s[2:3], 0, v[188:189]
	v_lshl_add_u64 v[176:177], v[176:177], 0, v[154:155]
	global_load_dwordx4 v[160:163], v[176:177], off
	global_load_dwordx4 v[164:167], v[176:177], off offset:64
	global_load_dwordx4 v[168:171], v[176:177], off offset:512
	global_load_dwordx4 v[172:175], v[176:177], off offset:576
	v_pk_fma_f32 v[46:47], v[46:47], v[138:139], v[58:59]
	v_pk_fma_f32 v[48:49], v[48:49], v[140:141], v[60:61]
	s_waitcnt vmcnt(4)
	v_pk_mul_f32 v[60:61], v[194:195], s[84:85] op_sel_hi:[1,0]
	v_pk_mul_f32 v[58:59], v[192:193], s[84:85] op_sel_hi:[1,0]
	v_pk_fma_f32 v[60:61], v[40:41], v[152:153], v[60:61]
	v_pk_fma_f32 v[58:59], v[38:39], v[150:151], v[58:59]
	v_pk_mul_f32 v[40:41], v[220:221], s[84:85] op_sel_hi:[1,0]
	v_pk_mul_f32 v[38:39], v[218:219], s[84:85] op_sel_hi:[1,0]
	v_pk_fma_f32 v[64:65], v[36:37], v[148:149], v[40:41]
	v_pk_fma_f32 v[62:63], v[34:35], v[146:147], v[38:39]
	v_pk_mul_f32 v[36:37], v[224:225], s[84:85] op_sel_hi:[1,0]
	v_pk_mul_f32 v[34:35], v[222:223], s[84:85] op_sel_hi:[1,0]
	v_pk_fma_f32 v[28:29], v[28:29], v[144:145], v[36:37]
	v_pk_fma_f32 v[26:27], v[26:27], v[142:143], v[34:35]
	v_pk_mul_f32 v[34:35], v[226:227], s[84:85] op_sel_hi:[1,0]
	v_pk_mul_f32 v[36:37], v[228:229], s[84:85] op_sel_hi:[1,0]
	v_lshl_add_u64 v[176:177], s[2:3], 0, v[182:183]
	v_lshl_add_u64 v[176:177], v[176:177], 0, v[154:155]
	global_load_dwordx4 v[192:195], v[176:177], off
	global_load_dwordx4 v[218:221], v[176:177], off offset:64
	global_load_dwordx4 v[222:225], v[176:177], off offset:512
	global_load_dwordx4 v[226:229], v[176:177], off offset:576
	v_pk_fma_f32 v[30:31], v[30:31], v[138:139], v[34:35]
	v_pk_fma_f32 v[32:33], v[32:33], v[140:141], v[36:37]
	s_waitcnt vmcnt(4)
; __device__ __forceinline__ float shx(float v, int mask, int lane) { return __int_as_float(__builtin_amdgcn_ds_bpermute((lane ^ mask) << 2, __float_as_int(v))); }
; #define EPI_ROWS(ai, m) _Pragma("unroll") for (int ai = 0; ai < 2; ++ai) _Pragma("unroll") for (int m = 0; m < 4; ++m)
; #define EPI_COLS(bj, n) _Pragma("unroll") for (int bj = 0; bj < 2; ++bj) _Pragma("unroll") for (int n = 0; n < 2; ++n)
;     __device__ __forceinline__ void run(const Acc& v, const Unit& u, int wr, int wc, int fr, int fq, LAS unsigned char* sl, int wid, int lane) const {
;     ...
;                 float sm = 0.f;
; #pragma unroll
;                 for (int bj = 0; bj < 2; ++bj)
; #pragma unroll
;                     for (int n = 0; n < 2; ++n) { const f32x4 x = v[ai][bj][m][n]; sm += (x[0] + x[1]) + (x[2] + x[3]); }
;                 sm += shx(sm, 16, lane); sm += shx(sm, 32, lane);
;                 const float mw = sm * (1.0f / 64.0f); float q = 0.f;
; #pragma unroll
;                 for (int bj = 0; bj < 2; ++bj)
; #pragma unroll
;                     for (int n = 0; n < 2; ++n) { const f32x4 d = v[ai][bj][m][n] - mw; q += (d[0] * d[0] + d[1] * d[1]) + (d[2] * d[2] + d[3] * d[3]); }
;                 q += shx(q, 16, lane); q += shx(q, 32, lane);
;                 if (fq == 0) P[(ai * 128 + wr * 64 + m * 16 + fr) * 4 + wc] = (f32x2){mw, q};
;     __device__ __forceinline__ void fused(Acc& acc, const Unit& u, int wr, int wc, int fr, int fq) const {
;     ...
;         EPI_ROWS(ai, m) { const int row = u.pm * 256 + ai * 128 + wr * 64 + m * 16 + fr; const float* hp = H + (size_t)row * D + colb;
;             EPI_COLS(bj, n) { const int co = bj * 128 + n * 16; acc[ai][bj][m][n] = *(const f32x4*)(hp + co) * ALPHA + gv[bj][n] * acc[ai][bj][m][n]; }
	v_pk_mul_f32 v[36:37], v[162:163], s[84:85] op_sel_hi:[1,0]
	v_pk_mul_f32 v[34:35], v[160:161], s[84:85] op_sel_hi:[1,0]
	v_pk_fma_f32 v[36:37], v[24:25], v[152:153], v[36:37]
	v_pk_fma_f32 v[34:35], v[22:23], v[150:151], v[34:35]
	v_pk_mul_f32 v[24:25], v[166:167], s[84:85] op_sel_hi:[1,0]
	v_pk_mul_f32 v[22:23], v[164:165], s[84:85] op_sel_hi:[1,0]
	v_pk_fma_f32 v[40:41], v[20:21], v[148:149], v[24:25]
	v_pk_fma_f32 v[38:39], v[18:19], v[146:147], v[22:23]
	v_pk_mul_f32 v[20:21], v[170:171], s[84:85] op_sel_hi:[1,0]
	v_pk_mul_f32 v[18:19], v[168:169], s[84:85] op_sel_hi:[1,0]
	v_pk_fma_f32 v[20:21], v[16:17], v[144:145], v[20:21]
	v_pk_fma_f32 v[18:19], v[14:15], v[142:143], v[18:19]
	v_pk_mul_f32 v[14:15], v[172:173], s[84:85] op_sel_hi:[1,0]
	v_pk_mul_f32 v[16:17], v[174:175], s[84:85] op_sel_hi:[1,0]
	v_pk_fma_f32 v[22:23], v[10:11], v[138:139], v[14:15]
	v_pk_fma_f32 v[24:25], v[12:13], v[140:141], v[16:17]
	s_waitcnt vmcnt(0)
	s_lshl_b32 s2, s59, 3
	s_add_i32 s14, s2, 0
	s_add_i32 s14, s14, 0x20000
	v_pk_mul_f32 v[12:13], v[194:195], s[84:85] op_sel_hi:[1,0]
	v_pk_mul_f32 v[10:11], v[192:193], s[84:85] op_sel_hi:[1,0]
	v_pk_fma_f32 v[16:17], v[136:137], v[152:153], v[12:13]
	v_pk_fma_f32 v[14:15], v[134:135], v[150:151], v[10:11]
	v_mov_b32_e32 v134, v123
	v_mov_b32_e32 v135, v124
	v_mov_b32_e32 v136, v122
	v_mov_b32_e32 v137, v125
	v_pk_add_f32 v[134:135], v[134:135], v[136:137]
	v_mov_b32_e32 v136, v127
	v_mov_b32_e32 v137, v128
	v_pk_mul_f32 v[12:13], v[220:221], s[84:85] op_sel_hi:[1,0]
	v_pk_mul_f32 v[10:11], v[218:219], s[84:85] op_sel_hi:[1,0]
	v_pk_fma_f32 v[12:13], v[132:133], v[148:149], v[12:13]
	v_pk_fma_f32 v[10:11], v[130:131], v[146:147], v[10:11]
	v_pk_mul_f32 v[132:133], v[224:225], s[84:85] op_sel_hi:[1,0]
	v_pk_mul_f32 v[130:131], v[222:223], s[84:85] op_sel_hi:[1,0]
	v_pk_fma_f32 v[8:9], v[8:9], v[144:145], v[132:133]
	v_pk_fma_f32 v[6:7], v[6:7], v[142:143], v[130:131]
	v_pk_mul_f32 v[130:131], v[226:227], s[84:85] op_sel_hi:[1,0]
	s_nop 0
	v_pk_fma_f32 v[2:3], v[2:3], v[138:139], v[130:131]
	v_mov_b32_e32 v138, v126
	v_mov_b32_e32 v139, v129
	v_pk_mul_f32 v[132:133], v[228:229], s[84:85] op_sel_hi:[1,0]
	v_pk_add_f32 v[136:137], v[136:137], v[138:139]
	v_pk_fma_f32 v[4:5], v[4:5], v[140:141], v[132:133]
	v_add_f32_e32 v133, v134, v135
	v_pk_add_f32 v[136:137], v[136:137], v[136:137] op_sel_hi:[0,1]
	v_add_f32_e32 v135, 0, v133
	v_add_f32_e32 v139, v98, v99
	v_add_f32_e32 v141, v100, v101
	v_mov_b32_e32 v138, v102
	v_mov_b32_e32 v140, v103
	v_mov_b32_e32 v136, v104
	v_mov_b32_e32 v134, v105
	v_lshl_add_u32 v132, v157, 4, v156
	v_pk_add_f32 v[138:139], v[138:139], v[140:141]
	v_pk_add_f32 v[134:135], v[136:137], v[134:135]
	v_lshlrev_b32_e32 v130, 2, v132
	v_pk_add_f32 v[134:135], v[138:139], v[134:135]
	v_xor_b32_e32 v131, 64, v130
	v_add_f32_e32 v133, v134, v135
	ds_bpermute_b32 v134, v131, v133
	v_xor_b32_e32 v130, 0x80, v130
	s_waitcnt lgkmcnt(0)
	v_add_f32_e32 v133, v133, v134
	ds_bpermute_b32 v134, v130, v133
	s_waitcnt lgkmcnt(0)
	v_add_f32_e32 v133, v133, v134
	v_fmamk_f32 v135, v133, 0xbc800000, v125
	v_fmamk_f32 v137, v133, 0xbc800000, v123
	v_fmamk_f32 v134, v133, 0xbc800000, v124
	v_fmamk_f32 v136, v133, 0xbc800000, v122
	v_mul_f32_e32 v137, v137, v137
	v_mul_f32_e32 v135, v135, v135
	v_fmac_f32_e32 v137, v136, v136
	v_fmac_f32_e32 v135, v134, v134
	v_fmamk_f32 v136, v133, 0xbc800000, v129
	v_fmamk_f32 v138, v133, 0xbc800000, v127
	v_add_f32_e32 v134, v137, v135
	v_fmamk_f32 v135, v133, 0xbc800000, v128
	v_fmamk_f32 v137, v133, 0xbc800000, v126
	v_mul_f32_e32 v138, v138, v138
	v_mul_f32_e32 v136, v136, v136
	v_fmac_f32_e32 v138, v137, v137
	v_fmac_f32_e32 v136, v135, v135
	v_add_f32_e32 v135, v138, v136
	v_fmamk_f32 v136, v133, 0xbc800000, v101
	v_fmamk_f32 v138, v133, 0xbc800000, v99
	v_add_f32_e32 v134, v134, v135
	v_fmamk_f32 v135, v133, 0xbc800000, v100
	v_fmamk_f32 v137, v133, 0xbc800000, v98
	v_mul_f32_e32 v138, v138, v138
	v_mul_f32_e32 v136, v136, v136
	v_fmac_f32_e32 v138, v137, v137
	v_fmac_f32_e32 v136, v135, v135
	v_add_f32_e32 v135, v138, v136
	v_fmamk_f32 v136, v133, 0xbc800000, v105
	v_fmamk_f32 v138, v133, 0xbc800000, v103
	v_add_f32_e32 v134, v135, v134
	v_fmamk_f32 v135, v133, 0xbc800000, v104
	v_fmamk_f32 v137, v133, 0xbc800000, v102
	v_mul_f32_e32 v138, v138, v138
	v_mul_f32_e32 v136, v136, v136
	v_fmac_f32_e32 v138, v137, v137
	v_fmac_f32_e32 v136, v135, v135
	v_add_f32_e32 v135, v138, v136
	v_add_f32_e32 v134, v135, v134
	ds_bpermute_b32 v135, v131, v134
	s_waitcnt lgkmcnt(0)
	v_add_f32_e32 v134, v134, v135
	ds_bpermute_b32 v135, v130, v134
	s_and_saveexec_b64 s[2:3], vcc
	s_cbranch_execz .LBB0_1863
	s_lshl_b32 s16, s5, 11
	s_add_i32 s16, s14, s16
	v_mul_f32_e32 v136, 0x3c800000, v133
	s_waitcnt lgkmcnt(0)
	v_add_f32_e32 v137, v134, v135
	v_lshl_add_u32 v133, v156, 5, s16
	ds_write_b64 v133, v[136:137]
